# hgrn stage 1 (layers with learned lower bound): next item's two lower-bound loads issued before the current item's stores; item head waits vmcnt(14) instead of load+drain
# baseline (speedup 1.0000x reference)
.LBB0_294:
	s_or_b64 exec, exec, s[6:7]
	s_nop 5
	v_cvt_pk_bf16_f32 v24, v24, s0
	v_cndmask_b32_e64 v24, v24, 0, s[14:15]
	ds_write_b16 v131, v24
	v_cvt_pk_bf16_f32 v24, v25, s0
	v_cndmask_b32_e64 v24, v24, 0, s[16:17]
	ds_write_b16 v132, v24
	v_cvt_pk_bf16_f32 v24, v26, s0
	v_cndmask_b32_e64 v24, v24, 0, s[18:19]
	ds_write_b16 v133, v24
	v_cvt_pk_bf16_f32 v24, v27, s0
	v_cndmask_b32_e64 v24, v24, 0, s[22:23]
	ds_write_b16 v134, v24
	ds_read_b128 v[28:31], v46 offset:52224
	ds_read_b128 v[24:27], v46 offset:52288
	ds_read_b128 v[60:63], v130
	ds_read_b128 v[64:67], v130 offset:64
	s_waitcnt lgkmcnt(1)
	v_mfma_f32_16x16x32_bf16 v[60:63], v[28:31], v[60:63], 0
	v_readlane_b32 s6, v247, 28
	v_readlane_b32 s7, v247, 29
	v_readlane_b32 s4, v247, 25
	s_waitcnt lgkmcnt(0)
	v_mfma_f32_16x16x32_bf16 v[60:63], v[24:27], v[64:67], v[60:63]
	v_lshl_add_u64 v[48:49], v[48:49], 0, s[6:7]
	ds_read_b128 v[66:69], v130 offset:2368
	v_readlane_b32 s6, v247, 32
	v_readlane_b32 s7, v247, 33
	s_add_i32 s30, s30, s4
	s_and_b64 s[100:101], exec, s[0:1]
	s_cbranch_scc0 .Llbp_skip_0
	s_and_b32 s100, s30, 0x180
	v_or_b32_e32 v184, s100, v33
	v_lshlrev_b32_e32 v184, 2, v184
	v_readlane_b32 s100, v250, 36
	v_readlane_b32 s101, v250, 37
	s_nop 4
	global_load_dwordx2 v[180:181], v184, s[100:101]
	global_load_dwordx2 v[182:183], v184, s[100:101] offset:2048
.Llbp_skip_0:
	s_nop 2
	v_cvt_pk_bf16_f32 v64, v60, v61
	v_cvt_pk_bf16_f32 v65, v62, v63
	v_lshl_add_u64 v[60:61], s[38:39], 0, v[50:51]
	global_store_dwordx2 v[60:61], v[64:65], off
	ds_read_b128 v[62:65], v130 offset:2304
	s_waitcnt lgkmcnt(0)
	v_mfma_f32_16x16x32_bf16 v[62:65], v[28:31], v[62:65], 0
	v_lshl_add_u64 v[50:51], v[50:51], 0, s[6:7]
	v_readlane_b32 s6, v247, 38
	v_readlane_b32 s7, v247, 39
	v_mfma_f32_16x16x32_bf16 v[62:65], v[24:27], v[66:69], v[62:65]
	ds_read_b128 v[66:69], v130 offset:4672
	v_readlane_b32 s4, v247, 37
	s_add_i32 s5, s5, s4
	s_andn2_b64 vcc, exec, s[26:27]
	s_nop 3
	v_cvt_pk_bf16_f32 v62, v62, v63
	v_cvt_pk_bf16_f32 v63, v64, v65
	global_store_dwordx2 v[60:61], v[62:63], off offset:512
	ds_read_b128 v[62:65], v130 offset:4608
	s_waitcnt lgkmcnt(0)
	v_mfma_f32_16x16x32_bf16 v[62:65], v[28:31], v[62:65], 0
	v_mfma_f32_16x16x32_bf16 v[62:65], v[24:27], v[66:69], v[62:65]
	ds_read_b128 v[66:69], v130 offset:6976
	s_nop 6
	v_cvt_pk_bf16_f32 v62, v62, v63
	v_cvt_pk_bf16_f32 v63, v64, v65
	global_store_dwordx2 v[60:61], v[62:63], off offset:1024
	ds_read_b128 v[62:65], v130 offset:6912
	s_waitcnt lgkmcnt(0)
	v_mfma_f32_16x16x32_bf16 v[62:65], v[28:31], v[62:65], 0
	v_mfma_f32_16x16x32_bf16 v[62:65], v[24:27], v[66:69], v[62:65]
	ds_read_b128 v[66:69], v130 offset:9280
	s_nop 6
	v_cvt_pk_bf16_f32 v62, v62, v63
	v_cvt_pk_bf16_f32 v63, v64, v65
	global_store_dwordx2 v[60:61], v[62:63], off offset:1536
	ds_read_b128 v[62:65], v130 offset:9216
	s_waitcnt lgkmcnt(0)
	v_mfma_f32_16x16x32_bf16 v[62:65], v[28:31], v[62:65], 0
	v_mfma_f32_16x16x32_bf16 v[62:65], v[24:27], v[66:69], v[62:65]
	ds_read_b128 v[66:69], v130 offset:11584
	s_nop 6
	v_cvt_pk_bf16_f32 v62, v62, v63
	v_cvt_pk_bf16_f32 v63, v64, v65
	global_store_dwordx2 v[60:61], v[62:63], off offset:2048
	ds_read_b128 v[62:65], v130 offset:11520
	s_waitcnt lgkmcnt(0)
	v_mfma_f32_16x16x32_bf16 v[62:65], v[28:31], v[62:65], 0
	v_mfma_f32_16x16x32_bf16 v[62:65], v[24:27], v[66:69], v[62:65]
	ds_read_b128 v[66:69], v130 offset:13888
	s_nop 6
	v_cvt_pk_bf16_f32 v62, v62, v63
	v_cvt_pk_bf16_f32 v63, v64, v65
	global_store_dwordx2 v[60:61], v[62:63], off offset:2560
	ds_read_b128 v[62:65], v130 offset:13824
	s_waitcnt lgkmcnt(0)
	v_mfma_f32_16x16x32_bf16 v[62:65], v[28:31], v[62:65], 0
	v_mfma_f32_16x16x32_bf16 v[62:65], v[24:27], v[66:69], v[62:65]
	v_lshl_add_u64 v[68:69], s[38:39], 0, v[52:53]
	v_lshl_add_u64 v[52:53], v[52:53], 0, s[6:7]
	s_nop 5
	v_cvt_pk_bf16_f32 v62, v62, v63
	v_cvt_pk_bf16_f32 v63, v64, v65
	global_store_dwordx2 v[60:61], v[62:63], off offset:3072
	ds_read_b128 v[62:65], v130 offset:16128
	s_waitcnt lgkmcnt(0)
	v_mfma_f32_16x16x32_bf16 v[28:31], v[28:31], v[62:65], 0
	ds_read_b128 v[62:65], v130 offset:16192
	s_waitcnt lgkmcnt(0)
	v_mfma_f32_16x16x32_bf16 v[24:27], v[24:27], v[62:65], v[28:31]
	s_nop 4
	v_lshl_add_u64 v[28:29], s[38:39], 0, v[56:57]
	v_lshl_add_u64 v[56:57], v[56:57], 0, s[6:7]
	s_nop 0
	v_cvt_pk_bf16_f32 v24, v24, v25
	v_cvt_pk_bf16_f32 v25, v26, v27
	global_store_dwordx2 v[60:61], v[24:25], off offset:3584
	ds_read_b128 v[24:27], v47 offset:34816
	s_waitcnt lgkmcnt(0)
	global_store_dwordx4 v[28:29], v[24:27], off
	ds_read_b128 v[24:27], v119 offset:34816
	v_lshl_add_u64 v[28:29], s[38:39], 0, v[58:59]
	v_lshl_add_u64 v[58:59], v[58:59], 0, s[6:7]
	s_waitcnt lgkmcnt(0)
	global_store_dwordx4 v[28:29], v[24:27], off
	s_waitcnt lgkmcnt(0)
	s_barrier
	ds_read_b128 v[24:27], v45
	ds_read_b128 v[28:31], v45 offset:64
	ds_read_b128 v[60:63], v138
	ds_read_b128 v[64:67], v138 offset:64
	s_waitcnt lgkmcnt(1)
	v_mfma_f32_16x16x32_bf16 v[60:63], v[24:27], v[60:63], 0
	s_waitcnt lgkmcnt(0)
	v_mfma_f32_16x16x32_bf16 v[60:63], v[28:31], v[64:67], v[60:63]
	ds_read_b128 v[64:67], v139 offset:64
	s_nop 6
	v_cvt_pk_bf16_f32 v60, v60, v61
	v_cvt_pk_bf16_f32 v61, v62, v63
	v_lshl_add_u64 v[62:63], s[38:39], 0, v[54:55]
	global_store_dwordx2 v[62:63], v[60:61], off
	ds_read_b128 v[60:63], v139
	s_waitcnt lgkmcnt(0)
	v_mfma_f32_16x16x32_bf16 v[60:63], v[24:27], v[60:63], 0
	v_lshl_add_u64 v[54:55], v[54:55], 0, s[6:7]
	v_mfma_f32_16x16x32_bf16 v[60:63], v[28:31], v[64:67], v[60:63]
	ds_read_b128 v[64:67], v140 offset:64
	s_nop 6
	v_cvt_pk_bf16_f32 v60, v60, v61
	v_cvt_pk_bf16_f32 v61, v62, v63
	global_store_dwordx2 v[68:69], v[60:61], off offset:-512
	ds_read_b128 v[60:63], v140
	s_waitcnt lgkmcnt(0)
	v_mfma_f32_16x16x32_bf16 v[60:63], v[24:27], v[60:63], 0
	v_mfma_f32_16x16x32_bf16 v[60:63], v[28:31], v[64:67], v[60:63]
	s_nop 7
	v_cvt_pk_bf16_f32 v60, v60, v61
	v_cvt_pk_bf16_f32 v61, v62, v63
	global_store_dwordx2 v[68:69], v[60:61], off
	ds_read_b128 v[60:63], v141
	s_waitcnt lgkmcnt(0)
	v_mfma_f32_16x16x32_bf16 v[24:27], v[24:27], v[60:63], 0
	ds_read_b128 v[60:63], v141 offset:64
	s_waitcnt lgkmcnt(0)
	v_mfma_f32_16x16x32_bf16 v[24:27], v[28:31], v[60:63], v[24:27]
	s_nop 7
	v_cvt_pk_bf16_f32 v24, v24, v25
	v_cvt_pk_bf16_f32 v25, v26, v27
	global_store_dwordx2 v[68:69], v[24:25], off offset:512
	s_waitcnt lgkmcnt(0)
	s_barrier
	s_cbranch_vccz .LBB0_305
	s_mov_b32 s98, 1
.LBB0_295:
	v_mov_b32_e32 v82, 0
	s_andn2_b64 vcc, exec, s[0:1]
	v_mov_b32_e32 v83, 0
	s_cbranch_vccnz .LBB0_297
	s_and_b32 s6, s30, 0x180
	s_cmp_lg_u32 s98, 0
	v_readlane_b32 s64, v250, 24
	v_or_b32_e32 v24, s6, v33
	v_readlane_b32 s65, v250, 25
	v_readlane_b32 s66, v250, 26
	v_readlane_b32 s67, v250, 27
	v_readlane_b32 s76, v250, 36
	v_readlane_b32 s77, v250, 37
	v_lshlrev_b32_e32 v26, 2, v24
	v_readlane_b32 s78, v250, 38
	v_readlane_b32 s79, v250, 39
	s_mov_b64 s[64:65], s[76:77]
	s_cbranch_scc1 .Llbt_skip_0
	global_load_dwordx2 v[24:25], v26, s[64:65]
	s_nop 0
	global_load_dwordx2 v[26:27], v26, s[64:65] offset:2048
.Llbt_skip_0:
	v_readlane_b32 s68, v250, 28
	v_readlane_b32 s69, v250, 29
	v_readlane_b32 s70, v250, 30
	v_readlane_b32 s71, v250, 31
	v_readlane_b32 s72, v250, 32
	v_readlane_b32 s73, v250, 33
	v_readlane_b32 s74, v250, 34
	v_readlane_b32 s75, v250, 35
	s_mov_b64 s[66:67], s[78:79]
	s_cbranch_scc1 .Llbt_pre_0
	s_waitcnt vmcnt(0)
	s_branch .Llbt_go_0
.Llbt_pre_0:
	s_waitcnt vmcnt(14)
	v_mov_b32_e32 v24, v180
	v_mov_b32_e32 v25, v181
	v_mov_b32_e32 v26, v182
	v_mov_b32_e32 v27, v183
.Llbt_go_0:
	v_sub_f32_e32 v24, v24, v26
	v_sub_f32_e32 v25, v25, v27
	v_mul_f32_e32 v24, 0x3fb8aa3b, v24
	v_mul_f32_e32 v25, 0x3fb8aa3b, v25
	v_exp_f32_e32 v24, v24
	v_exp_f32_e32 v25, v25
	s_nop 0
	v_pk_add_f32 v[24:25], v[24:25], 1.0 op_sel_hi:[1,0]
	s_nop 0
	v_div_scale_f32 v26, s[6:7], v24, v24, 1.0
	v_rcp_f32_e32 v27, v26
	s_nop 0
	v_fma_f32 v28, -v26, v27, 1.0
	v_fmac_f32_e32 v27, v28, v27
	v_div_scale_f32 v28, vcc, 1.0, v24, 1.0
	v_mul_f32_e32 v29, v28, v27
	v_fma_f32 v30, -v26, v29, v28
	v_fmac_f32_e32 v29, v30, v27
	v_fma_f32 v26, -v26, v29, v28
	v_div_fmas_f32 v26, v26, v27, v29
	v_div_fixup_f32 v82, v26, v24, 1.0
	v_div_scale_f32 v24, s[6:7], v25, v25, 1.0
	v_rcp_f32_e32 v26, v24
	s_nop 0
	v_fma_f32 v27, -v24, v26, 1.0
	v_fmac_f32_e32 v26, v27, v26
	v_div_scale_f32 v27, vcc, 1.0, v25, 1.0
	v_mul_f32_e32 v28, v27, v26
	v_fma_f32 v29, -v24, v28, v27
	v_fmac_f32_e32 v28, v29, v26
	v_fma_f32 v24, -v24, v28, v27
	v_div_fmas_f32 v24, v24, v26, v28
	v_div_fixup_f32 v83, v24, v25, 1.0

.LBB0_305:
	s_waitcnt vmcnt(0)
	s_mov_b64 s[0:1], 0
	s_barrier

.LBB0_309:
	s_or_b64 exec, exec, s[6:7]
	s_nop 5
	v_cvt_pk_bf16_f32 v24, v24, s0
	v_cndmask_b32_e64 v24, v24, 0, s[14:15]
	ds_write_b16 v131, v24
	v_cvt_pk_bf16_f32 v24, v25, s0
	v_cndmask_b32_e64 v24, v24, 0, s[16:17]
	ds_write_b16 v132, v24
	v_cvt_pk_bf16_f32 v24, v26, s0
	v_cndmask_b32_e64 v24, v24, 0, s[18:19]
	ds_write_b16 v133, v24
	v_cvt_pk_bf16_f32 v24, v27, s0
	v_cndmask_b32_e64 v24, v24, 0, s[22:23]
	ds_write_b16 v134, v24
	ds_read_b128 v[28:31], v46 offset:52224
	ds_read_b128 v[24:27], v46 offset:52288
	ds_read_b128 v[60:63], v130
	ds_read_b128 v[64:67], v130 offset:64
	s_waitcnt lgkmcnt(1)
	v_mfma_f32_16x16x32_bf16 v[60:63], v[28:31], v[60:63], 0
	s_mov_b64 s[6:7], 0x4000
	v_lshl_add_u64 v[48:49], v[48:49], 0, s[6:7]
	s_mov_b64 s[6:7], 0x100000
	s_waitcnt lgkmcnt(0)
	v_mfma_f32_16x16x32_bf16 v[60:63], v[24:27], v[64:67], v[60:63]
	s_add_i32 s30, s30, 64
	s_and_b64 s[100:101], exec, s[0:1]
	s_cbranch_scc0 .Llbp_skip_1
	s_and_b32 s100, s30, 0x180
	v_or_b32_e32 v184, s100, v33
	v_lshlrev_b32_e32 v184, 2, v184
	v_readlane_b32 s100, v250, 36
	v_readlane_b32 s101, v250, 37
	s_nop 4
	global_load_dwordx2 v[180:181], v184, s[100:101]
	global_load_dwordx2 v[182:183], v184, s[100:101] offset:2048
.Llbp_skip_1:
	ds_read_b128 v[66:69], v130 offset:2368
	s_addk_i32 s5, 0x800
	s_andn2_b64 vcc, exec, s[26:27]
	s_nop 3
	v_cvt_pk_bf16_f32 v64, v60, v61
	v_cvt_pk_bf16_f32 v65, v62, v63
	v_lshl_add_u64 v[60:61], s[38:39], 0, v[50:51]
	global_store_dwordx2 v[60:61], v[64:65], off
	ds_read_b128 v[62:65], v130 offset:2304
	s_waitcnt lgkmcnt(0)
	v_mfma_f32_16x16x32_bf16 v[62:65], v[28:31], v[62:65], 0
	v_lshl_add_u64 v[50:51], v[50:51], 0, s[6:7]
	s_mov_b32 s6, s31
	v_mfma_f32_16x16x32_bf16 v[62:65], v[24:27], v[66:69], v[62:65]
	ds_read_b128 v[66:69], v130 offset:4672
	s_nop 6
	v_cvt_pk_bf16_f32 v62, v62, v63
	v_cvt_pk_bf16_f32 v63, v64, v65
	global_store_dwordx2 v[60:61], v[62:63], off offset:512
	ds_read_b128 v[62:65], v130 offset:4608
	s_waitcnt lgkmcnt(0)
	v_mfma_f32_16x16x32_bf16 v[62:65], v[28:31], v[62:65], 0
	v_mfma_f32_16x16x32_bf16 v[62:65], v[24:27], v[66:69], v[62:65]
	ds_read_b128 v[66:69], v130 offset:6976
	s_nop 6
	v_cvt_pk_bf16_f32 v62, v62, v63
	v_cvt_pk_bf16_f32 v63, v64, v65
	global_store_dwordx2 v[60:61], v[62:63], off offset:1024
	ds_read_b128 v[62:65], v130 offset:6912
	s_waitcnt lgkmcnt(0)
	v_mfma_f32_16x16x32_bf16 v[62:65], v[28:31], v[62:65], 0
	v_mfma_f32_16x16x32_bf16 v[62:65], v[24:27], v[66:69], v[62:65]
	ds_read_b128 v[66:69], v130 offset:9280
	s_nop 6
	v_cvt_pk_bf16_f32 v62, v62, v63
	v_cvt_pk_bf16_f32 v63, v64, v65
	global_store_dwordx2 v[60:61], v[62:63], off offset:1536
	ds_read_b128 v[62:65], v130 offset:9216
	s_waitcnt lgkmcnt(0)
	v_mfma_f32_16x16x32_bf16 v[62:65], v[28:31], v[62:65], 0
	v_mfma_f32_16x16x32_bf16 v[62:65], v[24:27], v[66:69], v[62:65]
	ds_read_b128 v[66:69], v130 offset:11584
	s_nop 6
	v_cvt_pk_bf16_f32 v62, v62, v63
	v_cvt_pk_bf16_f32 v63, v64, v65
	global_store_dwordx2 v[60:61], v[62:63], off offset:2048
	ds_read_b128 v[62:65], v130 offset:11520
	s_waitcnt lgkmcnt(0)
	v_mfma_f32_16x16x32_bf16 v[62:65], v[28:31], v[62:65], 0
	v_mfma_f32_16x16x32_bf16 v[62:65], v[24:27], v[66:69], v[62:65]
	ds_read_b128 v[66:69], v130 offset:13888
	s_nop 6
	v_cvt_pk_bf16_f32 v62, v62, v63
	v_cvt_pk_bf16_f32 v63, v64, v65
	global_store_dwordx2 v[60:61], v[62:63], off offset:2560
	ds_read_b128 v[62:65], v130 offset:13824
	s_waitcnt lgkmcnt(0)
	v_mfma_f32_16x16x32_bf16 v[62:65], v[28:31], v[62:65], 0
	v_mfma_f32_16x16x32_bf16 v[62:65], v[24:27], v[66:69], v[62:65]
	v_lshl_add_u64 v[68:69], s[38:39], 0, v[52:53]
	v_lshl_add_u64 v[52:53], v[52:53], 0, s[28:29]
	s_nop 5
	v_cvt_pk_bf16_f32 v62, v62, v63
	v_cvt_pk_bf16_f32 v63, v64, v65
	global_store_dwordx2 v[60:61], v[62:63], off offset:3072
	ds_read_b128 v[62:65], v130 offset:16128
	s_waitcnt lgkmcnt(0)
	v_mfma_f32_16x16x32_bf16 v[28:31], v[28:31], v[62:65], 0
	ds_read_b128 v[62:65], v130 offset:16192
	s_waitcnt lgkmcnt(0)
	v_mfma_f32_16x16x32_bf16 v[24:27], v[24:27], v[62:65], v[28:31]
	s_nop 4
	v_lshl_add_u64 v[28:29], s[38:39], 0, v[56:57]
	v_lshl_add_u64 v[56:57], v[56:57], 0, s[28:29]
	s_nop 0
	v_cvt_pk_bf16_f32 v24, v24, v25
	v_cvt_pk_bf16_f32 v25, v26, v27
	global_store_dwordx2 v[60:61], v[24:25], off offset:3584
	ds_read_b128 v[24:27], v47 offset:34816
	s_waitcnt lgkmcnt(0)
	global_store_dwordx4 v[28:29], v[24:27], off
	ds_read_b128 v[24:27], v119 offset:34816
	v_lshl_add_u64 v[28:29], s[38:39], 0, v[58:59]
	v_lshl_add_u64 v[58:59], v[58:59], 0, s[28:29]
	s_waitcnt lgkmcnt(0)
	global_store_dwordx4 v[28:29], v[24:27], off
	s_waitcnt lgkmcnt(0)
	s_barrier
	ds_read_b128 v[24:27], v45
	ds_read_b128 v[28:31], v45 offset:64
	ds_read_b128 v[60:63], v138
	ds_read_b128 v[64:67], v138 offset:64
	s_waitcnt lgkmcnt(1)
	v_mfma_f32_16x16x32_bf16 v[60:63], v[24:27], v[60:63], 0
	s_waitcnt lgkmcnt(0)
	v_mfma_f32_16x16x32_bf16 v[60:63], v[28:31], v[64:67], v[60:63]
	ds_read_b128 v[64:67], v139 offset:64
	s_nop 6
	v_cvt_pk_bf16_f32 v60, v60, v61
	v_cvt_pk_bf16_f32 v61, v62, v63
	v_lshl_add_u64 v[62:63], s[38:39], 0, v[54:55]
	global_store_dwordx2 v[62:63], v[60:61], off
	ds_read_b128 v[60:63], v139
	s_waitcnt lgkmcnt(0)
	v_mfma_f32_16x16x32_bf16 v[60:63], v[24:27], v[60:63], 0
	v_lshl_add_u64 v[54:55], v[54:55], 0, s[28:29]
	v_mfma_f32_16x16x32_bf16 v[60:63], v[28:31], v[64:67], v[60:63]
	ds_read_b128 v[64:67], v140 offset:64
	s_nop 6
	v_cvt_pk_bf16_f32 v60, v60, v61
	v_cvt_pk_bf16_f32 v61, v62, v63
	global_store_dwordx2 v[68:69], v[60:61], off offset:-512
	ds_read_b128 v[60:63], v140
	s_waitcnt lgkmcnt(0)
	v_mfma_f32_16x16x32_bf16 v[60:63], v[24:27], v[60:63], 0
	v_mfma_f32_16x16x32_bf16 v[60:63], v[28:31], v[64:67], v[60:63]
	s_nop 7
	v_cvt_pk_bf16_f32 v60, v60, v61
	v_cvt_pk_bf16_f32 v61, v62, v63
	global_store_dwordx2 v[68:69], v[60:61], off
	ds_read_b128 v[60:63], v141
	s_waitcnt lgkmcnt(0)
	v_mfma_f32_16x16x32_bf16 v[24:27], v[24:27], v[60:63], 0
	ds_read_b128 v[60:63], v141 offset:64
	s_waitcnt lgkmcnt(0)
	v_mfma_f32_16x16x32_bf16 v[24:27], v[28:31], v[60:63], v[24:27]
	s_nop 7
	v_cvt_pk_bf16_f32 v24, v24, v25
	v_cvt_pk_bf16_f32 v25, v26, v27
	global_store_dwordx2 v[68:69], v[24:25], off offset:512
	s_waitcnt lgkmcnt(0)
	s_barrier
	s_cbranch_vccz .LBB0_320
	s_mov_b32 s98, 1
.LBB0_310:
	v_mov_b32_e32 v82, 0
	s_andn2_b64 vcc, exec, s[0:1]
	v_mov_b32_e32 v83, 0
	s_cbranch_vccnz .LBB0_312
	s_and_b32 s7, s30, 0x180
	s_cmp_lg_u32 s98, 0
	v_readlane_b32 s64, v250, 24
	v_or_b32_e32 v24, s7, v33
	v_readlane_b32 s65, v250, 25
	v_readlane_b32 s66, v250, 26
	v_readlane_b32 s67, v250, 27
	v_readlane_b32 s76, v250, 36
	v_readlane_b32 s77, v250, 37
	v_lshlrev_b32_e32 v26, 2, v24
	v_readlane_b32 s78, v250, 38
	v_readlane_b32 s79, v250, 39
	s_mov_b64 s[64:65], s[76:77]
	s_cbranch_scc1 .Llbt_skip_1
	global_load_dwordx2 v[24:25], v26, s[64:65]
	s_nop 0
	global_load_dwordx2 v[26:27], v26, s[64:65] offset:2048

.Llbt_go_1:
	v_sub_f32_e32 v24, v24, v26
	v_sub_f32_e32 v25, v25, v27
	v_mul_f32_e32 v24, 0x3fb8aa3b, v24
	v_mul_f32_e32 v25, 0x3fb8aa3b, v25
	v_exp_f32_e32 v24, v24
	v_exp_f32_e32 v25, v25
	s_nop 0
	v_pk_add_f32 v[24:25], v[24:25], 1.0 op_sel_hi:[1,0]
	s_nop 0
	v_div_scale_f32 v26, s[26:27], v24, v24, 1.0
	v_rcp_f32_e32 v27, v26
	s_nop 0
	v_fma_f32 v28, -v26, v27, 1.0
	v_fmac_f32_e32 v27, v28, v27
	v_div_scale_f32 v28, vcc, 1.0, v24, 1.0
	v_mul_f32_e32 v29, v28, v27
	v_fma_f32 v30, -v26, v29, v28
	v_fmac_f32_e32 v29, v30, v27
	v_fma_f32 v26, -v26, v29, v28
	v_div_fmas_f32 v26, v26, v27, v29
	v_div_fixup_f32 v82, v26, v24, 1.0
	v_div_scale_f32 v24, s[26:27], v25, v25, 1.0
	v_rcp_f32_e32 v26, v24
	s_nop 0
	v_fma_f32 v27, -v24, v26, 1.0
	v_fmac_f32_e32 v26, v27, v26
	v_div_scale_f32 v27, vcc, 1.0, v25, 1.0
	v_mul_f32_e32 v28, v27, v26
	v_fma_f32 v29, -v24, v28, v27
	v_fmac_f32_e32 v28, v29, v26
	v_fma_f32 v24, -v24, v28, v27
	v_div_fmas_f32 v24, v24, v26, v28
	v_div_fixup_f32 v83, v24, v25, 1.0

.LBB0_318:
	s_or_b64 exec, exec, s[6:7]
	s_nop 6
	v_cvt_pk_bf16_f32 v25, v26, s0
	v_cndmask_b32_e64 v25, v25, 0, s[2:3]
	ds_write_b16 v137, v25
	v_cvt_pk_bf16_f32 v25, v27, s0
	v_cndmask_b32_e64 v25, v25, 0, s[10:11]
	ds_write_b16 v137, v25 offset:144
	v_cvt_pk_bf16_f32 v25, v28, s0
	v_cndmask_b32_e64 v25, v25, 0, s[12:13]
	ds_write_b16 v137, v25 offset:288
	v_cvt_pk_bf16_f32 v25, v29, s0
	v_cndmask_b32_e64 v25, v25, 0, s[8:9]
	ds_write_b16 v137, v25 offset:432
	v_mov_b32_e32 v25, 0
	v_mov_b32_e32 v26, 0
	v_mov_b32_e32 v27, 0
	s_and_saveexec_b64 s[6:7], s[60:61]
	s_cbranch_execz .LBB0_309
	ds_read_b128 v[24:27], v44
	ds_read_b128 v[28:31], v142 offset:21760
	s_waitcnt lgkmcnt(0)
	v_mfma_f32_16x16x32_bf16 v[24:27], v[24:27], v[28:31], 0
	ds_read_b128 v[28:31], v44 offset:64
	ds_read_b128 v[60:63], v142 offset:21824
	s_waitcnt lgkmcnt(0)
	v_mfma_f32_16x16x32_bf16 v[24:27], v[28:31], v[60:63], v[24:27]
	ds_read_b128 v[28:31], v44 offset:128
	ds_read_b128 v[60:63], v142 offset:21888
	s_waitcnt lgkmcnt(0)
	v_mfma_f32_16x16x32_bf16 v[24:27], v[28:31], v[60:63], v[24:27]
	ds_read_b128 v[28:31], v44 offset:192
	ds_read_b128 v[60:63], v142 offset:21952
	s_waitcnt lgkmcnt(0)
	v_mfma_f32_16x16x32_bf16 v[24:27], v[28:31], v[60:63], v[24:27]
	s_branch .LBB0_309
.LBB0_320:
	s_waitcnt vmcnt(0)
	s_barrier
.LBB0_321:
	v_readlane_b32 s0, v248, 45
	v_readlane_b32 s1, v248, 46
	s_andn2_b64 vcc, exec, s[0:1]
	s_cbranch_vccnz .LBB0_467
	v_readlane_b32 s0, v246, 32
	v_readlane_b32 s1, v246, 33
	v_readlane_b32 s4, v246, 38
	s_lshr_b64 s[0:1], s[0:1], 1
	s_lshl_b32 s24, s4, 11
	s_lshl_b64 s[6:7], s[0:1], 11
	s_lshl_b64 s[0:1], s[0:1], 17
	s_lshl_b64 s[2:3], s[24:25], 2
	v_readlane_b32 s40, v250, 40
	v_readlane_b32 s41, v250, 41
	s_add_u32 s26, s40, s2
	s_addc_u32 s27, s41, s3
	s_lshl_b32 s24, s4, 9
	v_readlane_b32 s42, v250, 42
	s_lshl_b64 s[8:9], s[24:25], 2
	v_readlane_b32 s43, v250, 43
	s_add_u32 s2, s42, s8
	s_addc_u32 s3, s43, s9
	s_lshl_b32 s24, s4, 15
	v_readlane_b32 s44, v250, 44
	v_writelane_b32 v246, s2, 43
	s_lshl_b64 s[10:11], s[24:25], 2
	v_readlane_b32 s45, v250, 45
	v_writelane_b32 v246, s3, 44
	s_add_u32 s2, s44, s10
	v_readlane_b32 s46, v250, 46
	s_addc_u32 s3, s45, s11
	v_readlane_b32 s47, v250, 47
	s_add_u32 s4, s46, s8
	v_readlane_b32 s48, v250, 48
	s_addc_u32 s5, s47, s9
	v_readlane_b32 s49, v250, 49
	s_add_u32 s22, s48, s10
	v_readlane_b32 s50, v250, 50
	v_writelane_b32 v246, s4, 45
	s_addc_u32 s23, s49, s11
	v_readlane_b32 s51, v250, 51
	v_writelane_b32 v246, s5, 46
	s_add_u32 s4, s50, s8
	s_addc_u32 s5, s51, s9
	v_readlane_b32 s52, v250, 52
	v_writelane_b32 v246, s4, 47
	v_readlane_b32 s53, v250, 53
	v_readlane_b32 s54, v250, 54
	v_writelane_b32 v246, s5, 48
	s_add_u32 s4, s52, s8
	s_addc_u32 s5, s53, s9
	v_writelane_b32 v246, s4, 49
	v_readlane_b32 s55, v250, 55
	s_nop 0
	v_writelane_b32 v246, s5, 50
	v_readlane_b32 s4, v247, 63
	s_add_u32 s4, s4, s6
	s_nop 0
	v_writelane_b32 v246, s4, 51
	s_nop 0
	v_readlane_b32 s4, v246, 0
	s_addc_u32 s4, s4, s7
	s_nop 0
	v_writelane_b32 v246, s4, 52
	s_add_u32 s4, s48, s0
	s_addc_u32 s5, s49, s1
	v_writelane_b32 v246, s4, 53
	s_nop 1
	v_writelane_b32 v246, s5, 54
	s_add_u32 s4, s44, s0
	s_addc_u32 s5, s45, s1
	v_writelane_b32 v246, s4, 55
	s_nop 1
	v_writelane_b32 v246, s5, 56
	s_nop 0
	v_readlane_b32 s4, v246, 1
	s_add_u32 s6, s4, s0
	v_readlane_b32 s4, v246, 2
	s_addc_u32 s7, s4, s1
	v_writelane_b32 v246, s6, 57
	s_nop 1
	v_writelane_b32 v246, s7, 58
	s_nop 0
	v_readlane_b32 s4, v246, 3
	s_add_u32 s4, s4, s0
	v_readlane_b32 s0, v246, 4
	s_addc_u32 s5, s0, s1
	v_writelane_b32 v246, s4, 59
	s_nop 1
	v_writelane_b32 v246, s5, 60
	s_nop 0
	v_readlane_b32 s0, v246, 36
	v_readlane_b32 s1, v246, 37
	s_add_u32 s0, s0, 0x2fcc00
	v_writelane_b32 v246, s0, 61
	s_addc_u32 s0, s1, 0
	v_writelane_b32 v246, s0, 62
	s_nop 0
	v_readlane_b32 s18, v246, 6
	v_readlane_b32 s24, v246, 5
	s_branch .LBB0_324
